# EpiSwiglu rstd batching: 8 ssq loads at epilogue head in both FFN up phases, one reduce block
# baseline (speedup 1.0000x reference)
; __device__ __forceinline__ void row_rstd4(const float* ssq, int row0, int fq, float (&rs)[4]) {
;     f32x4 v[4];
; #pragma unroll
;     for (int m = 0; m < 4; ++m) v[m] = *(const f32x4*)(ssq + (size_t)(row0 + m * 16) * 16 + fq * 4);
; #pragma unroll
;     for (int m = 0; m < 4; ++m) { float t = (v[m][0] + v[m][1]) + (v[m][2] + v[m][3]); t += __shfl_xor(t, 16); t += __shfl_xor(t, 32); rs[m] = __builtin_amdgcn_rsqf(t * (1.f / DM) + EPS); }
; }
;     __device__ __forceinline__ void operator()(const f32x4 (&acc)[2][2][4][2], const pg8::Unit& u, int wr, int wc, int fr, int fq) const {
;         const int row0 = u.pm * 256 + wr * 64 + fr, col0 = u.pn * 128 + wc * 32 + 8 * fq;
; #pragma unroll
;         for (int ai = 0; ai < 2; ++ai) { float rsv[4]; row_rstd4(ssq, row0 + ai * 128, fq, rsv);
; #pragma unroll
;             for (int m = 0; m < 4; ++m) {
;                 const int row = row0 + ai * 128 + m * 16; const float rs = rsv[m], c = -rs * LOG2E, rs2 = rs * rs;
;                 f32x4 e0 = acc[ai][0][m][0] * c, e1 = acc[ai][0][m][1] * c;
; #pragma unroll
;                 for (int i = 0; i < 4; ++i) { e0[i] = __builtin_amdgcn_exp2f(e0[i]); e1[i] = __builtin_amdgcn_exp2f(e1[i]); }
;                 e0 = e0 + 1.0f; e1 = e1 + 1.0f;
; #pragma unroll
;                 for (int i = 0; i < 4; ++i) { e0[i] = __builtin_amdgcn_rcpf(e0[i]); e1[i] = __builtin_amdgcn_rcpf(e1[i]); }
;                 const f32x4 h0 = (acc[ai][0][m][0] * acc[ai][1][m][0]) * rs2 * e0, h1 = (acc[ai][0][m][1] * acc[ai][1][m][1]) * rs2 * e1;
.LBB0_159:
	v_lshl_add_u32 v240, s24, 8, v148
	v_mov_b32_e32 v172, v240
	v_ashrrev_i32_e32 v173, 31, v172
	v_lshlrev_b64 v[172:173], 6, v[172:173]
	v_lshl_add_u64 v[172:173], v[134:135], 0, v[172:173]
	global_load_dwordx4 v[172:175], v[172:173], off
	v_add_u32_e32 v176, 16, v240
	v_ashrrev_i32_e32 v177, 31, v176
	v_lshlrev_b64 v[176:177], 6, v[176:177]
	v_lshl_add_u64 v[176:177], v[134:135], 0, v[176:177]
	global_load_dwordx4 v[176:179], v[176:177], off
	v_add_u32_e32 v180, 32, v240
	v_ashrrev_i32_e32 v181, 31, v180
	v_lshlrev_b64 v[180:181], 6, v[180:181]
	v_lshl_add_u64 v[180:181], v[134:135], 0, v[180:181]
	global_load_dwordx4 v[180:183], v[180:181], off
	v_add_u32_e32 v184, 48, v240
	v_ashrrev_i32_e32 v185, 31, v184
	v_lshlrev_b64 v[184:185], 6, v[184:185]
	v_lshl_add_u64 v[184:185], v[134:135], 0, v[184:185]
	global_load_dwordx4 v[184:187], v[184:185], off
	v_add_u32_e32 v188, 0x80, v240
	v_ashrrev_i32_e32 v189, 31, v188
	v_lshlrev_b64 v[188:189], 6, v[188:189]
	v_lshl_add_u64 v[188:189], v[134:135], 0, v[188:189]
	global_load_dwordx4 v[188:191], v[188:189], off
	v_add_u32_e32 v218, 0x90, v240
	v_ashrrev_i32_e32 v219, 31, v218
	v_lshlrev_b64 v[218:219], 6, v[218:219]
	v_lshl_add_u64 v[218:219], v[134:135], 0, v[218:219]
	global_load_dwordx4 v[218:221], v[218:219], off
	v_add_u32_e32 v222, 0xa0, v240
	v_ashrrev_i32_e32 v223, 31, v222
	v_lshlrev_b64 v[222:223], 6, v[222:223]
	v_lshl_add_u64 v[222:223], v[134:135], 0, v[222:223]
	global_load_dwordx4 v[222:225], v[222:223], off
	v_add_u32_e32 v226, 0xb0, v240
	v_ashrrev_i32_e32 v227, 31, v226
	v_lshlrev_b64 v[226:227], 6, v[226:227]
	v_lshl_add_u64 v[226:227], v[134:135], 0, v[226:227]
	global_load_dwordx4 v[226:229], v[226:227], off
	v_xor_b32_e32 v238, 16, v215
	v_xor_b32_e32 v239, 32, v215
	v_lshlrev_b32_e32 v238, 2, v238
	v_lshlrev_b32_e32 v239, 2, v239
	v_lshl_add_u32 v140, s24, 8, v148
	v_or_b32_e32 v146, 16, v140
	v_ashrrev_i32_e32 v141, 31, v140
	v_ashrrev_i32_e32 v147, 31, v146
	v_lshlrev_b64 v[142:143], 6, v[140:141]
	v_lshlrev_b64 v[144:145], 6, v[146:147]
	v_lshl_add_u64 v[142:143], v[134:135], 0, v[142:143]
	v_lshl_add_u64 v[144:145], v[134:135], 0, v[144:145]
	s_nop 0
	s_nop 0
	v_or_b32_e32 v144, 32, v140
	v_ashrrev_i32_e32 v145, 31, v144
	v_lshlrev_b64 v[142:143], 6, v[144:145]
	v_lshl_add_u64 v[142:143], v[134:135], 0, v[142:143]
	s_nop 0
	v_or_b32_e32 v142, 48, v140
	v_ashrrev_i32_e32 v143, 31, v142
	v_lshlrev_b64 v[164:165], 6, v[142:143]
	v_lshl_add_u64 v[164:165], v[134:135], 0, v[164:165]
	s_nop 0
	v_and_b32_e32 v143, 64, v215
	v_xor_b32_e32 v141, 16, v215
	v_add_u32_e32 v143, 64, v143
	v_xor_b32_e32 v145, 32, v215
	v_cmp_lt_i32_e32 vcc, v141, v143
	v_pk_mul_f32 v[126:127], v[118:119], v[126:127]
	v_pk_mul_f32 v[124:125], v[116:117], v[124:125]
	v_cndmask_b32_e32 v141, v215, v141, vcc
	v_cmp_lt_i32_e32 vcc, v145, v143
	v_lshlrev_b32_e32 v141, 2, v141
	v_pk_mul_f32 v[120:121], v[112:113], v[120:121]
	v_cndmask_b32_e32 v143, v215, v145, vcc
	v_lshlrev_b32_e32 v143, 2, v143
	v_pk_mul_f32 v[122:123], v[114:115], v[122:123]
	v_lshl_or_b32 v168, s70, 7, v150
	v_ashrrev_i32_e32 v169, 31, v168
	v_pk_mul_f32 v[100:101], v[108:109], v[100:101]
	v_pk_mul_f32 v[102:103], v[110:111], v[102:103]
	v_pk_mul_f32 v[98:99], v[106:107], v[98:99]
	v_pk_mul_f32 v[96:97], v[104:105], v[96:97]
	v_pk_mul_f32 v[84:85], v[92:93], v[84:85]
	v_pk_mul_f32 v[86:87], v[94:95], v[86:87]
	v_pk_mul_f32 v[82:83], v[90:91], v[82:83]
	v_pk_mul_f32 v[80:81], v[88:89], v[80:81]
	v_pk_mul_f32 v[68:69], v[76:77], v[68:69]
	v_pk_mul_f32 v[70:71], v[78:79], v[70:71]
	v_pk_mul_f32 v[66:67], v[74:75], v[66:67]
	v_pk_mul_f32 v[64:65], v[72:73], v[64:65]
	v_pk_mul_f32 v[52:53], v[60:61], v[52:53]
	v_pk_mul_f32 v[54:55], v[62:63], v[54:55]
	v_pk_mul_f32 v[50:51], v[58:59], v[50:51]
	v_pk_mul_f32 v[48:49], v[56:57], v[48:49]
	v_pk_mul_f32 v[36:37], v[44:45], v[36:37]
	v_pk_mul_f32 v[38:39], v[46:47], v[38:39]
	v_pk_mul_f32 v[34:35], v[42:43], v[34:35]
	v_pk_mul_f32 v[32:33], v[40:41], v[32:33]
	v_pk_mul_f32 v[20:21], v[28:29], v[20:21]
	v_pk_mul_f32 v[22:23], v[30:31], v[22:23]
	v_pk_mul_f32 v[18:19], v[26:27], v[18:19]
	v_pk_mul_f32 v[16:17], v[24:25], v[16:17]
	v_pk_mul_f32 v[4:5], v[12:13], v[4:5]
	v_pk_mul_f32 v[6:7], v[14:15], v[6:7]
	v_pk_mul_f32 v[2:3], v[10:11], v[2:3]
	v_pk_mul_f32 v[0:1], v[8:9], v[0:1]
	s_andn2_b64 vcc, exec, s[4:5]
	s_mov_b64 s[4:5], -1
	s_waitcnt vmcnt(0)
	v_add_f32_e32 v172, v172, v173
	v_add_f32_e32 v174, v174, v175
	v_add_f32_e32 v176, v176, v177
	v_add_f32_e32 v178, v178, v179
	v_add_f32_e32 v180, v180, v181
	v_add_f32_e32 v182, v182, v183
	v_add_f32_e32 v184, v184, v185
	v_add_f32_e32 v186, v186, v187
	v_add_f32_e32 v188, v188, v189
	v_add_f32_e32 v190, v190, v191
	v_add_f32_e32 v218, v218, v219
	v_add_f32_e32 v220, v220, v221
	v_add_f32_e32 v222, v222, v223
	v_add_f32_e32 v224, v224, v225
	v_add_f32_e32 v226, v226, v227
	v_add_f32_e32 v228, v228, v229
	v_add_f32_e32 v172, v172, v174
	v_add_f32_e32 v176, v176, v178
	v_add_f32_e32 v180, v180, v182
	v_add_f32_e32 v184, v184, v186
	v_add_f32_e32 v188, v188, v190
	v_add_f32_e32 v218, v218, v220
	v_add_f32_e32 v222, v222, v224
	v_add_f32_e32 v226, v226, v228
	ds_bpermute_b32 v173, v238, v172
	ds_bpermute_b32 v177, v238, v176
	ds_bpermute_b32 v181, v238, v180
	ds_bpermute_b32 v185, v238, v184
	ds_bpermute_b32 v189, v238, v188
	ds_bpermute_b32 v219, v238, v218
	ds_bpermute_b32 v223, v238, v222
	ds_bpermute_b32 v227, v238, v226
	s_waitcnt lgkmcnt(0)
; __device__ __forceinline__ v4u pack8(const f32x4 a, const f32x4 b) { v4u w; w.x = cvt_pk_bf16(a[0], a[1]); w.y = cvt_pk_bf16(a[2], a[3]); w.z = cvt_pk_bf16(b[0], b[1]); w.w = cvt_pk_bf16(b[2], b[3]); return w; }
;     __device__ __forceinline__ void operator()(const f32x4 (&acc)[2][2][4][2], const pg8::Unit& u, int wr, int wc, int fr, int fq) const {
;     ...
;         for (int ai = 0; ai < 2; ++ai) { float rsv[4]; row_rstd4(ssq, row0 + ai * 128, fq, rsv);
; #pragma unroll
;             for (int m = 0; m < 4; ++m) {
;                 const int row = row0 + ai * 128 + m * 16; const float rs = rsv[m], c = -rs * LOG2E, rs2 = rs * rs;
;                 f32x4 e0 = acc[ai][0][m][0] * c, e1 = acc[ai][0][m][1] * c;
; #pragma unroll
;                 for (int i = 0; i < 4; ++i) { e0[i] = __builtin_amdgcn_exp2f(e0[i]); e1[i] = __builtin_amdgcn_exp2f(e1[i]); }
;                 e0 = e0 + 1.0f; e1 = e1 + 1.0f;
; #pragma unroll
;                 for (int i = 0; i < 4; ++i) { e0[i] = __builtin_amdgcn_rcpf(e0[i]); e1[i] = __builtin_amdgcn_rcpf(e1[i]); }
;                 const f32x4 h0 = (acc[ai][0][m][0] * acc[ai][1][m][0]) * rs2 * e0, h1 = (acc[ai][0][m][1] * acc[ai][1][m][1]) * rs2 * e1;
;                 *(v4u*)(O + (size_t)row * FFH + col0) = pack8(h0, h1);
	v_add_f32_e32 v172, v172, v173
	v_add_f32_e32 v176, v176, v177
	v_add_f32_e32 v180, v180, v181
	v_add_f32_e32 v184, v184, v185
	v_add_f32_e32 v188, v188, v189
	v_add_f32_e32 v218, v218, v219
	v_add_f32_e32 v222, v222, v223
	v_add_f32_e32 v226, v226, v227
	ds_bpermute_b32 v173, v239, v172
	ds_bpermute_b32 v177, v239, v176
	ds_bpermute_b32 v181, v239, v180
	ds_bpermute_b32 v185, v239, v184
	ds_bpermute_b32 v189, v239, v188
	ds_bpermute_b32 v219, v239, v218
	ds_bpermute_b32 v223, v239, v222
	ds_bpermute_b32 v227, v239, v226
	s_waitcnt lgkmcnt(0)
	v_add_f32_e32 v172, v172, v173
	v_add_f32_e32 v176, v176, v177
	v_add_f32_e32 v180, v180, v181
	v_add_f32_e32 v184, v184, v185
	v_add_f32_e32 v188, v188, v189
	v_add_f32_e32 v218, v218, v219
	v_add_f32_e32 v222, v222, v223
	v_add_f32_e32 v226, v226, v227
	v_fmamk_f32 v172, v172, 0x3a800000, v212
	v_fmamk_f32 v176, v176, 0x3a800000, v212
	v_fmamk_f32 v180, v180, 0x3a800000, v212
	v_fmamk_f32 v184, v184, 0x3a800000, v212
	v_fmamk_f32 v188, v188, 0x3a800000, v212
	v_fmamk_f32 v218, v218, 0x3a800000, v212
	v_fmamk_f32 v222, v222, 0x3a800000, v212
	v_fmamk_f32 v226, v226, 0x3a800000, v212
	v_rsq_f32_e32 v230, v172
	v_rsq_f32_e32 v231, v176
	v_rsq_f32_e32 v232, v180
	v_rsq_f32_e32 v233, v184
	v_rsq_f32_e32 v234, v188
	v_rsq_f32_e32 v235, v218
	v_rsq_f32_e32 v236, v222
	v_rsq_f32_e32 v237, v226
	s_nop 0
	s_waitcnt lgkmcnt(0)
	s_nop 0
	s_nop 0
	s_nop 0
	s_nop 0
	s_nop 0
	s_nop 0
	s_nop 0
	s_nop 0
	s_nop 0
	s_nop 0
	s_nop 0
	s_nop 0
	s_nop 0
	s_nop 0
	s_nop 0
	s_nop 0
	s_nop 0
	s_nop 0
	s_nop 0
	s_nop 0
	s_nop 0
	s_nop 0
	s_nop 0
	s_nop 0
	s_waitcnt lgkmcnt(0)
	s_nop 0
	s_nop 0
	s_waitcnt lgkmcnt(0)
	s_nop 0
	s_waitcnt lgkmcnt(0)
	s_nop 0
	s_waitcnt lgkmcnt(0)
	s_nop 0
	s_nop 0
	s_nop 0
	s_nop 0
	s_waitcnt lgkmcnt(0)
	s_nop 0
	s_nop 0
	s_waitcnt lgkmcnt(0)
	s_nop 0
	s_waitcnt lgkmcnt(0)
	s_nop 0
	s_waitcnt lgkmcnt(0)
	s_nop 0
	v_mov_b32_e32 v145, v230
	s_nop 0
	v_mov_b32_e32 v153, v233
	s_nop 0
	v_mov_b32_e32 v155, v232
	v_mul_f32_e32 v152, 0xbfb8aa3b, v145
	v_pk_mul_f32 v[118:119], v[118:119], v[152:153] op_sel_hi:[1,0]
	v_pk_mul_f32 v[116:117], v[116:117], v[152:153] op_sel_hi:[1,0]
	v_pk_mul_f32 v[112:113], v[112:113], v[152:153] op_sel_hi:[1,0]
	v_pk_mul_f32 v[114:115], v[114:115], v[152:153] op_sel_hi:[1,0]
	v_exp_f32_e32 v116, v116
	v_exp_f32_e32 v112, v112
	v_exp_f32_e32 v117, v117
	v_exp_f32_e32 v118, v118
	v_exp_f32_e32 v119, v119
	v_exp_f32_e32 v113, v113
	v_exp_f32_e32 v114, v114
	v_exp_f32_e32 v115, v115
	v_pk_add_f32 v[118:119], v[118:119], 1.0 op_sel_hi:[1,0]
	v_pk_add_f32 v[116:117], v[116:117], 1.0 op_sel_hi:[1,0]
	v_pk_add_f32 v[112:113], v[112:113], 1.0 op_sel_hi:[1,0]
	v_pk_add_f32 v[114:115], v[114:115], 1.0 op_sel_hi:[1,0]
	v_rcp_f32_e32 v116, v116
	v_rcp_f32_e32 v112, v112
	v_rcp_f32_e32 v117, v117
	v_rcp_f32_e32 v118, v118
	v_rcp_f32_e32 v119, v119
	v_rcp_f32_e32 v113, v113
	v_rcp_f32_e32 v114, v114
	v_rcp_f32_e32 v115, v115
	v_mul_f32_e32 v154, v145, v145
	s_nop 0
	v_pk_mul_f32 v[124:125], v[124:125], v[154:155] op_sel_hi:[1,0]
	v_pk_mul_f32 v[126:127], v[126:127], v[154:155] op_sel_hi:[1,0]
	v_pk_mul_f32 v[120:121], v[120:121], v[154:155] op_sel_hi:[1,0]
	v_mov_b32_e32 v147, v231
	v_pk_mul_f32 v[122:123], v[122:123], v[154:155] op_sel_hi:[1,0]
	v_pk_mul_f32 v[118:119], v[126:127], v[118:119]
	v_pk_mul_f32 v[116:117], v[124:125], v[116:117]
	v_pk_mul_f32 v[112:113], v[120:121], v[112:113]
	v_pk_mul_f32 v[114:115], v[122:123], v[114:115]
	v_cvt_pk_bf16_f32 v116, v116, v117
	v_cvt_pk_bf16_f32 v117, v118, v119
	v_cvt_pk_bf16_f32 v118, v112, v113
	v_mov_b64_e32 v[112:113], s[12:13]
	v_cvt_pk_bf16_f32 v119, v114, v115
	v_mad_i64_i32 v[120:121], s[8:9], v140, s3, v[112:113]
	v_lshlrev_b64 v[114:115], 1, v[168:169]
	v_lshl_add_u64 v[120:121], v[120:121], 0, v[114:115]
	global_store_dwordx4 v[120:121], v[116:119], off
	v_mul_f32_e32 v124, v147, v147
	v_pk_mul_f32 v[100:101], v[100:101], v[124:125] op_sel_hi:[1,0]
	v_mul_f32_e32 v116, 0xbfb8aa3b, v147
	v_pk_mul_f32 v[120:121], v[108:109], v[116:117] op_sel_hi:[1,0]
	v_pk_mul_f32 v[118:119], v[110:111], v[116:117] op_sel_hi:[1,0]
	v_pk_mul_f32 v[122:123], v[106:107], v[116:117] op_sel_hi:[1,0]
	v_pk_mul_f32 v[116:117], v[104:105], v[116:117] op_sel_hi:[1,0]
	v_exp_f32_e32 v120, v120
	v_exp_f32_e32 v121, v121
	v_exp_f32_e32 v116, v116
	v_exp_f32_e32 v118, v118
	v_exp_f32_e32 v119, v119
	v_exp_f32_e32 v122, v122
	v_exp_f32_e32 v123, v123
	v_exp_f32_e32 v117, v117
	v_pk_add_f32 v[120:121], v[120:121], 1.0 op_sel_hi:[1,0]
	v_pk_add_f32 v[118:119], v[118:119], 1.0 op_sel_hi:[1,0]
	v_pk_add_f32 v[122:123], v[122:123], 1.0 op_sel_hi:[1,0]
	v_pk_add_f32 v[116:117], v[116:117], 1.0 op_sel_hi:[1,0]
	v_rcp_f32_e32 v120, v120
	v_rcp_f32_e32 v121, v121
	v_rcp_f32_e32 v116, v116
	v_rcp_f32_e32 v117, v117
	v_rcp_f32_e32 v118, v118
	v_rcp_f32_e32 v122, v122
	v_rcp_f32_e32 v119, v119
	v_rcp_f32_e32 v123, v123
	v_pk_mul_f32 v[102:103], v[102:103], v[124:125] op_sel_hi:[1,0]
	v_pk_mul_f32 v[100:101], v[100:101], v[120:121]
	v_pk_mul_f32 v[96:97], v[96:97], v[124:125] op_sel_hi:[1,0]
	v_pk_mul_f32 v[98:99], v[98:99], v[124:125] op_sel_hi:[1,0]
	v_pk_mul_f32 v[102:103], v[102:103], v[118:119]
	v_pk_mul_f32 v[104:105], v[98:99], v[122:123]
	v_pk_mul_f32 v[98:99], v[96:97], v[116:117]
	v_cvt_pk_bf16_f32 v96, v100, v101
	v_mad_i64_i32 v[100:101], s[8:9], v146, s3, v[112:113]
	v_cvt_pk_bf16_f32 v97, v102, v103
	v_cvt_pk_bf16_f32 v98, v98, v99
	v_cvt_pk_bf16_f32 v99, v104, v105
	v_lshl_add_u64 v[100:101], v[100:101], 0, v[114:115]
	global_store_dwordx4 v[100:101], v[96:99], off
	v_mul_f32_e32 v104, v155, v155
	v_pk_mul_f32 v[84:85], v[84:85], v[104:105] op_sel_hi:[1,0]
; __device__ __forceinline__ v4u pack8(const f32x4 a, const f32x4 b) { v4u w; w.x = cvt_pk_bf16(a[0], a[1]); w.y = cvt_pk_bf16(a[2], a[3]); w.z = cvt_pk_bf16(b[0], b[1]); w.w = cvt_pk_bf16(b[2], b[3]); return w; }
; __device__ __forceinline__ void row_rstd4(const float* ssq, int row0, int fq, float (&rs)[4]) {
;     ...
;     for (int m = 0; m < 4; ++m) v[m] = *(const f32x4*)(ssq + (size_t)(row0 + m * 16) * 16 + fq * 4);
; #pragma unroll
;     for (int m = 0; m < 4; ++m) { float t = (v[m][0] + v[m][1]) + (v[m][2] + v[m][3]); t += __shfl_xor(t, 16); t += __shfl_xor(t, 32); rs[m] = __builtin_amdgcn_rsqf(t * (1.f / DM) + EPS); }
;     __device__ __forceinline__ void operator()(const f32x4 (&acc)[2][2][4][2], const pg8::Unit& u, int wr, int wc, int fr, int fq) const {
;     ...
;                 const int row = row0 + ai * 128 + m * 16; const float rs = rsv[m], c = -rs * LOG2E, rs2 = rs * rs;
;                 f32x4 e0 = acc[ai][0][m][0] * c, e1 = acc[ai][0][m][1] * c;
; #pragma unroll
;                 for (int i = 0; i < 4; ++i) { e0[i] = __builtin_amdgcn_exp2f(e0[i]); e1[i] = __builtin_amdgcn_exp2f(e1[i]); }
;                 e0 = e0 + 1.0f; e1 = e1 + 1.0f;
; #pragma unroll
;                 for (int i = 0; i < 4; ++i) { e0[i] = __builtin_amdgcn_rcpf(e0[i]); e1[i] = __builtin_amdgcn_rcpf(e1[i]); }
;                 const f32x4 h0 = (acc[ai][0][m][0] * acc[ai][1][m][0]) * rs2 * e0, h1 = (acc[ai][0][m][1] * acc[ai][1][m][1]) * rs2 * e1;
;                 *(v4u*)(O + (size_t)row * FFH + col0) = pack8(h0, h1);
	v_mul_f32_e32 v96, 0xbfb8aa3b, v155
	v_pk_mul_f32 v[100:101], v[92:93], v[96:97] op_sel_hi:[1,0]
	v_pk_mul_f32 v[98:99], v[94:95], v[96:97] op_sel_hi:[1,0]
	v_pk_mul_f32 v[102:103], v[90:91], v[96:97] op_sel_hi:[1,0]
	v_pk_mul_f32 v[96:97], v[88:89], v[96:97] op_sel_hi:[1,0]
	v_exp_f32_e32 v100, v100
	v_exp_f32_e32 v101, v101
	v_exp_f32_e32 v96, v96
	v_exp_f32_e32 v98, v98
	v_exp_f32_e32 v99, v99
	v_exp_f32_e32 v102, v102
	v_exp_f32_e32 v103, v103
	v_exp_f32_e32 v97, v97
	v_pk_add_f32 v[100:101], v[100:101], 1.0 op_sel_hi:[1,0]
	v_pk_add_f32 v[98:99], v[98:99], 1.0 op_sel_hi:[1,0]
	v_pk_add_f32 v[102:103], v[102:103], 1.0 op_sel_hi:[1,0]
	v_pk_add_f32 v[96:97], v[96:97], 1.0 op_sel_hi:[1,0]
	v_rcp_f32_e32 v100, v100
	v_rcp_f32_e32 v101, v101
	v_rcp_f32_e32 v96, v96
	v_rcp_f32_e32 v97, v97
	v_rcp_f32_e32 v98, v98
	v_rcp_f32_e32 v102, v102
	v_rcp_f32_e32 v99, v99
	v_rcp_f32_e32 v103, v103
	v_pk_mul_f32 v[86:87], v[86:87], v[104:105] op_sel_hi:[1,0]
	v_pk_mul_f32 v[84:85], v[84:85], v[100:101]
	v_pk_mul_f32 v[80:81], v[80:81], v[104:105] op_sel_hi:[1,0]
	v_pk_mul_f32 v[82:83], v[82:83], v[104:105] op_sel_hi:[1,0]
	v_pk_mul_f32 v[86:87], v[86:87], v[98:99]
	v_pk_mul_f32 v[88:89], v[82:83], v[102:103]
	v_pk_mul_f32 v[82:83], v[80:81], v[96:97]
	v_cvt_pk_bf16_f32 v80, v84, v85
	v_mad_i64_i32 v[84:85], s[8:9], v144, s3, v[112:113]
	v_cvt_pk_bf16_f32 v81, v86, v87
	v_cvt_pk_bf16_f32 v82, v82, v83
	v_cvt_pk_bf16_f32 v83, v88, v89
	v_lshl_add_u64 v[84:85], v[84:85], 0, v[114:115]
	global_store_dwordx4 v[84:85], v[80:83], off
	v_mul_f32_e32 v88, v153, v153
	v_pk_mul_f32 v[68:69], v[68:69], v[88:89] op_sel_hi:[1,0]
	v_mul_f32_e32 v80, 0xbfb8aa3b, v153
	v_pk_mul_f32 v[84:85], v[76:77], v[80:81] op_sel_hi:[1,0]
	v_pk_mul_f32 v[82:83], v[78:79], v[80:81] op_sel_hi:[1,0]
	v_pk_mul_f32 v[86:87], v[74:75], v[80:81] op_sel_hi:[1,0]
	v_pk_mul_f32 v[80:81], v[72:73], v[80:81] op_sel_hi:[1,0]
	v_exp_f32_e32 v84, v84
	v_exp_f32_e32 v85, v85
	v_exp_f32_e32 v80, v80
	v_exp_f32_e32 v82, v82
	v_exp_f32_e32 v83, v83
	v_exp_f32_e32 v86, v86
	v_exp_f32_e32 v87, v87
	v_exp_f32_e32 v81, v81
	v_pk_add_f32 v[84:85], v[84:85], 1.0 op_sel_hi:[1,0]
	v_pk_add_f32 v[82:83], v[82:83], 1.0 op_sel_hi:[1,0]
	v_pk_add_f32 v[86:87], v[86:87], 1.0 op_sel_hi:[1,0]
	v_pk_add_f32 v[80:81], v[80:81], 1.0 op_sel_hi:[1,0]
	v_rcp_f32_e32 v84, v84
	v_rcp_f32_e32 v85, v85
	v_rcp_f32_e32 v80, v80
	v_rcp_f32_e32 v81, v81
	v_rcp_f32_e32 v82, v82
	v_rcp_f32_e32 v86, v86
	v_rcp_f32_e32 v83, v83
	v_rcp_f32_e32 v87, v87
	v_pk_mul_f32 v[70:71], v[70:71], v[88:89] op_sel_hi:[1,0]
	v_pk_mul_f32 v[68:69], v[68:69], v[84:85]
	v_pk_mul_f32 v[64:65], v[64:65], v[88:89] op_sel_hi:[1,0]
	v_pk_mul_f32 v[66:67], v[66:67], v[88:89] op_sel_hi:[1,0]
	v_pk_mul_f32 v[70:71], v[70:71], v[82:83]
	v_pk_mul_f32 v[72:73], v[66:67], v[86:87]
	v_pk_mul_f32 v[66:67], v[64:65], v[80:81]
	v_cvt_pk_bf16_f32 v64, v68, v69
	v_mad_i64_i32 v[68:69], s[8:9], v142, s3, v[112:113]
	v_add_u32_e32 v84, 0x80, v140
	v_cvt_pk_bf16_f32 v65, v70, v71
	v_cvt_pk_bf16_f32 v66, v66, v67
	v_cvt_pk_bf16_f32 v67, v72, v73
	v_lshl_add_u64 v[68:69], v[68:69], 0, v[114:115]
	v_ashrrev_i32_e32 v85, 31, v84
	global_store_dwordx4 v[68:69], v[64:67], off
	v_add_u32_e32 v86, 0x90, v140
	v_ashrrev_i32_e32 v87, 31, v86
	v_lshlrev_b64 v[64:65], 6, v[84:85]
	v_lshl_add_u64 v[64:65], v[134:135], 0, v[64:65]
	s_nop 0
	v_lshlrev_b64 v[64:65], 6, v[86:87]
	v_lshl_add_u64 v[64:65], v[134:135], 0, v[64:65]
	s_nop 0
	v_add_u32_e32 v66, 0xa0, v140
	v_ashrrev_i32_e32 v67, 31, v66
	v_lshlrev_b64 v[64:65], 6, v[66:67]
	v_lshl_add_u64 v[64:65], v[134:135], 0, v[64:65]
	s_nop 0
	v_add_u32_e32 v64, 0xb0, v140
	v_ashrrev_i32_e32 v65, 31, v64
	v_lshlrev_b64 v[80:81], 6, v[64:65]
	v_lshl_add_u64 v[80:81], v[134:135], 0, v[80:81]
	s_nop 0
	s_waitcnt lgkmcnt(0)
	s_nop 0
	s_nop 0
	s_nop 0
	s_nop 0
	s_nop 0
	s_nop 0
	s_nop 0
	s_nop 0
	s_nop 0
	s_nop 0
	s_nop 0
	s_waitcnt lgkmcnt(0)
	s_nop 0
	s_nop 0
	s_nop 0
	s_nop 0
	s_waitcnt lgkmcnt(0)
	s_nop 0
	s_waitcnt lgkmcnt(0)
	s_nop 0
	s_nop 0
	s_nop 0
	s_nop 0
	s_nop 0
	s_nop 0
	s_nop 0
	s_nop 0
	s_nop 0
	s_nop 0
	s_nop 0
	s_nop 0
	s_nop 0
	s_nop 0
	s_waitcnt lgkmcnt(0)
	s_nop 0
	s_nop 0
	s_waitcnt lgkmcnt(0)
	s_nop 0
	s_nop 0
	s_waitcnt lgkmcnt(0)
	s_nop 0
	s_nop 0
	v_mov_b32_e32 v65, v234
	s_nop 0
	s_waitcnt lgkmcnt(0)
	s_nop 0
	s_nop 0
	s_waitcnt lgkmcnt(0)
; __device__ __forceinline__ v4u pack8(const f32x4 a, const f32x4 b) { v4u w; w.x = cvt_pk_bf16(a[0], a[1]); w.y = cvt_pk_bf16(a[2], a[3]); w.z = cvt_pk_bf16(b[0], b[1]); w.w = cvt_pk_bf16(b[2], b[3]); return w; }
;     __device__ __forceinline__ void operator()(const f32x4 (&acc)[2][2][4][2], const pg8::Unit& u, int wr, int wc, int fr, int fq) const {
;     ...
;                 const int row = row0 + ai * 128 + m * 16; const float rs = rsv[m], c = -rs * LOG2E, rs2 = rs * rs;
;                 f32x4 e0 = acc[ai][0][m][0] * c, e1 = acc[ai][0][m][1] * c;
; #pragma unroll
;                 for (int i = 0; i < 4; ++i) { e0[i] = __builtin_amdgcn_exp2f(e0[i]); e1[i] = __builtin_amdgcn_exp2f(e1[i]); }
;                 e0 = e0 + 1.0f; e1 = e1 + 1.0f;
; #pragma unroll
;                 for (int i = 0; i < 4; ++i) { e0[i] = __builtin_amdgcn_rcpf(e0[i]); e1[i] = __builtin_amdgcn_rcpf(e1[i]); }
;                 const f32x4 h0 = (acc[ai][0][m][0] * acc[ai][1][m][0]) * rs2 * e0, h1 = (acc[ai][0][m][1] * acc[ai][1][m][1]) * rs2 * e1;
;                 *(v4u*)(O + (size_t)row * FFH + col0) = pack8(h0, h1);
	s_nop 0
	s_nop 0
	v_mov_b32_e32 v78, v237
	v_mul_f32_e32 v68, 0xbfb8aa3b, v65
	v_pk_mul_f32 v[72:73], v[60:61], v[68:69] op_sel_hi:[1,0]
	v_mov_b32_e32 v77, v236
	v_pk_mul_f32 v[70:71], v[62:63], v[68:69] op_sel_hi:[1,0]
	v_pk_mul_f32 v[74:75], v[58:59], v[68:69] op_sel_hi:[1,0]
	v_pk_mul_f32 v[68:69], v[56:57], v[68:69] op_sel_hi:[1,0]
	v_exp_f32_e32 v72, v72
	v_exp_f32_e32 v73, v73
	v_exp_f32_e32 v68, v68
	v_exp_f32_e32 v70, v70
	v_exp_f32_e32 v71, v71
	v_exp_f32_e32 v74, v74
	v_exp_f32_e32 v75, v75
	v_exp_f32_e32 v69, v69
	v_pk_add_f32 v[72:73], v[72:73], 1.0 op_sel_hi:[1,0]
	v_pk_add_f32 v[70:71], v[70:71], 1.0 op_sel_hi:[1,0]
	v_pk_add_f32 v[74:75], v[74:75], 1.0 op_sel_hi:[1,0]
	v_pk_add_f32 v[68:69], v[68:69], 1.0 op_sel_hi:[1,0]
	v_rcp_f32_e32 v72, v72
	v_rcp_f32_e32 v73, v73
	v_rcp_f32_e32 v68, v68
	v_rcp_f32_e32 v69, v69
	v_rcp_f32_e32 v70, v70
	v_rcp_f32_e32 v74, v74
	v_rcp_f32_e32 v71, v71
	v_rcp_f32_e32 v75, v75
	v_mul_f32_e32 v76, v65, v65
	v_mov_b32_e32 v67, v235
	v_pk_mul_f32 v[52:53], v[52:53], v[76:77] op_sel_hi:[1,0]
	v_pk_mul_f32 v[54:55], v[54:55], v[76:77] op_sel_hi:[1,0]
	v_pk_mul_f32 v[52:53], v[52:53], v[72:73]
	v_pk_mul_f32 v[48:49], v[48:49], v[76:77] op_sel_hi:[1,0]
	v_pk_mul_f32 v[50:51], v[50:51], v[76:77] op_sel_hi:[1,0]
	v_pk_mul_f32 v[54:55], v[54:55], v[70:71]
	v_pk_mul_f32 v[56:57], v[50:51], v[74:75]
	v_pk_mul_f32 v[50:51], v[48:49], v[68:69]
	v_cvt_pk_bf16_f32 v48, v52, v53
	v_mad_i64_i32 v[52:53], s[8:9], v84, s3, v[112:113]
	v_cvt_pk_bf16_f32 v49, v54, v55
	v_cvt_pk_bf16_f32 v50, v50, v51
	v_cvt_pk_bf16_f32 v51, v56, v57
	v_lshl_add_u64 v[52:53], v[52:53], 0, v[114:115]
	global_store_dwordx4 v[52:53], v[48:51], off
	v_mul_f32_e32 v56, v67, v67
	v_pk_mul_f32 v[36:37], v[36:37], v[56:57] op_sel_hi:[1,0]
	v_mul_f32_e32 v48, 0xbfb8aa3b, v67
	v_pk_mul_f32 v[52:53], v[44:45], v[48:49] op_sel_hi:[1,0]
	v_pk_mul_f32 v[50:51], v[46:47], v[48:49] op_sel_hi:[1,0]
	v_pk_mul_f32 v[54:55], v[42:43], v[48:49] op_sel_hi:[1,0]
	v_pk_mul_f32 v[48:49], v[40:41], v[48:49] op_sel_hi:[1,0]
	v_exp_f32_e32 v52, v52
	v_exp_f32_e32 v53, v53
	v_exp_f32_e32 v48, v48
	v_exp_f32_e32 v50, v50
	v_exp_f32_e32 v51, v51
	v_exp_f32_e32 v54, v54
	v_exp_f32_e32 v55, v55
	v_exp_f32_e32 v49, v49
	v_pk_add_f32 v[52:53], v[52:53], 1.0 op_sel_hi:[1,0]
	v_pk_add_f32 v[50:51], v[50:51], 1.0 op_sel_hi:[1,0]
	v_pk_add_f32 v[54:55], v[54:55], 1.0 op_sel_hi:[1,0]
	v_pk_add_f32 v[48:49], v[48:49], 1.0 op_sel_hi:[1,0]
	v_rcp_f32_e32 v52, v52
	v_rcp_f32_e32 v53, v53
	v_rcp_f32_e32 v48, v48
	v_rcp_f32_e32 v49, v49
	v_rcp_f32_e32 v50, v50
	v_rcp_f32_e32 v54, v54
	v_rcp_f32_e32 v51, v51
	v_rcp_f32_e32 v55, v55
	v_pk_mul_f32 v[38:39], v[38:39], v[56:57] op_sel_hi:[1,0]
	v_pk_mul_f32 v[36:37], v[36:37], v[52:53]
	v_pk_mul_f32 v[32:33], v[32:33], v[56:57] op_sel_hi:[1,0]
	v_pk_mul_f32 v[34:35], v[34:35], v[56:57] op_sel_hi:[1,0]
	v_pk_mul_f32 v[38:39], v[38:39], v[50:51]
	v_pk_mul_f32 v[40:41], v[34:35], v[54:55]
	v_pk_mul_f32 v[34:35], v[32:33], v[48:49]
	v_cvt_pk_bf16_f32 v32, v36, v37
	v_mad_i64_i32 v[36:37], s[8:9], v86, s3, v[112:113]
	v_cvt_pk_bf16_f32 v33, v38, v39
	v_cvt_pk_bf16_f32 v34, v34, v35
	v_cvt_pk_bf16_f32 v35, v40, v41
	v_lshl_add_u64 v[36:37], v[36:37], 0, v[114:115]
	global_store_dwordx4 v[36:37], v[32:35], off
	v_mul_f32_e32 v40, v77, v77
	v_pk_mul_f32 v[20:21], v[20:21], v[40:41] op_sel_hi:[1,0]
	v_mul_f32_e32 v32, 0xbfb8aa3b, v77
	v_pk_mul_f32 v[36:37], v[28:29], v[32:33] op_sel_hi:[1,0]
	v_pk_mul_f32 v[34:35], v[30:31], v[32:33] op_sel_hi:[1,0]
	v_pk_mul_f32 v[38:39], v[26:27], v[32:33] op_sel_hi:[1,0]
	v_pk_mul_f32 v[32:33], v[24:25], v[32:33] op_sel_hi:[1,0]
	v_exp_f32_e32 v36, v36
	v_exp_f32_e32 v37, v37
	v_exp_f32_e32 v32, v32
	v_exp_f32_e32 v34, v34
	v_exp_f32_e32 v35, v35
	v_exp_f32_e32 v38, v38
	v_exp_f32_e32 v39, v39
	v_exp_f32_e32 v33, v33
	v_pk_add_f32 v[36:37], v[36:37], 1.0 op_sel_hi:[1,0]
	v_pk_add_f32 v[34:35], v[34:35], 1.0 op_sel_hi:[1,0]
	v_pk_add_f32 v[38:39], v[38:39], 1.0 op_sel_hi:[1,0]
	v_pk_add_f32 v[32:33], v[32:33], 1.0 op_sel_hi:[1,0]
	v_rcp_f32_e32 v36, v36
	v_rcp_f32_e32 v37, v37
	v_rcp_f32_e32 v32, v32
	v_rcp_f32_e32 v33, v33
	v_rcp_f32_e32 v34, v34
	v_rcp_f32_e32 v38, v38
	v_rcp_f32_e32 v35, v35
	v_rcp_f32_e32 v39, v39
	v_pk_mul_f32 v[22:23], v[22:23], v[40:41] op_sel_hi:[1,0]
	v_pk_mul_f32 v[20:21], v[20:21], v[36:37]
	v_pk_mul_f32 v[16:17], v[16:17], v[40:41] op_sel_hi:[1,0]
	v_pk_mul_f32 v[18:19], v[18:19], v[40:41] op_sel_hi:[1,0]
	v_pk_mul_f32 v[22:23], v[22:23], v[34:35]
	v_pk_mul_f32 v[24:25], v[18:19], v[38:39]
	v_pk_mul_f32 v[18:19], v[16:17], v[32:33]
	v_cvt_pk_bf16_f32 v16, v20, v21
	v_mad_i64_i32 v[20:21], s[8:9], v66, s3, v[112:113]
	v_cvt_pk_bf16_f32 v17, v22, v23
	v_cvt_pk_bf16_f32 v18, v18, v19
	v_cvt_pk_bf16_f32 v19, v24, v25
	v_lshl_add_u64 v[20:21], v[20:21], 0, v[114:115]
	global_store_dwordx4 v[20:21], v[16:19], off
	v_mul_f32_e32 v24, v78, v78
	v_pk_mul_f32 v[4:5], v[4:5], v[24:25] op_sel_hi:[1,0]
	v_mul_f32_e32 v16, 0xbfb8aa3b, v78
	v_pk_mul_f32 v[20:21], v[12:13], v[16:17] op_sel_hi:[1,0]
	v_pk_mul_f32 v[18:19], v[14:15], v[16:17] op_sel_hi:[1,0]
	v_pk_mul_f32 v[22:23], v[10:11], v[16:17] op_sel_hi:[1,0]
	v_pk_mul_f32 v[16:17], v[8:9], v[16:17] op_sel_hi:[1,0]
	v_exp_f32_e32 v20, v20
	v_exp_f32_e32 v21, v21
	v_exp_f32_e32 v16, v16
	v_exp_f32_e32 v18, v18
	v_exp_f32_e32 v19, v19
	v_exp_f32_e32 v22, v22
	v_exp_f32_e32 v23, v23
	v_exp_f32_e32 v17, v17
	v_pk_add_f32 v[20:21], v[20:21], 1.0 op_sel_hi:[1,0]
	v_pk_add_f32 v[18:19], v[18:19], 1.0 op_sel_hi:[1,0]
	v_pk_add_f32 v[22:23], v[22:23], 1.0 op_sel_hi:[1,0]
	v_pk_add_f32 v[16:17], v[16:17], 1.0 op_sel_hi:[1,0]
	v_rcp_f32_e32 v20, v20
	v_rcp_f32_e32 v21, v21
	v_rcp_f32_e32 v16, v16
	v_rcp_f32_e32 v17, v17
	v_rcp_f32_e32 v18, v18
	v_rcp_f32_e32 v22, v22
	v_rcp_f32_e32 v19, v19
	v_rcp_f32_e32 v23, v23
	v_pk_mul_f32 v[6:7], v[6:7], v[24:25] op_sel_hi:[1,0]
	v_pk_mul_f32 v[4:5], v[4:5], v[20:21]
	v_pk_mul_f32 v[0:1], v[0:1], v[24:25] op_sel_hi:[1,0]
	v_pk_mul_f32 v[2:3], v[2:3], v[24:25] op_sel_hi:[1,0]
	v_pk_mul_f32 v[6:7], v[6:7], v[18:19]
	v_pk_mul_f32 v[8:9], v[2:3], v[22:23]
	v_pk_mul_f32 v[2:3], v[0:1], v[16:17]
	v_cvt_pk_bf16_f32 v0, v4, v5
	v_mad_i64_i32 v[4:5], s[8:9], v64, s3, v[112:113]
	v_cvt_pk_bf16_f32 v1, v6, v7
	v_cvt_pk_bf16_f32 v2, v2, v3
	v_cvt_pk_bf16_f32 v3, v8, v9
	v_lshl_add_u64 v[4:5], v[4:5], 0, v[114:115]
	global_store_dwordx4 v[4:5], v[0:3], off
	s_cbranch_vccnz .LBB0_152
	s_andn2_b64 vcc, exec, s[10:11]
	s_cbranch_vccnz .LBB0_151
	s_barrier
	s_branch .LBB0_151

; __device__ __forceinline__ void row_rstd4(const float* ssq, int row0, int fq, float (&rs)[4]) {
;     f32x4 v[4];
; #pragma unroll
;     for (int m = 0; m < 4; ++m) v[m] = *(const f32x4*)(ssq + (size_t)(row0 + m * 16) * 16 + fq * 4);
; #pragma unroll
;     for (int m = 0; m < 4; ++m) { float t = (v[m][0] + v[m][1]) + (v[m][2] + v[m][3]); t += __shfl_xor(t, 16); t += __shfl_xor(t, 32); rs[m] = __builtin_amdgcn_rsqf(t * (1.f / DM) + EPS); }
; }
;     __device__ __forceinline__ void operator()(const f32x4 (&acc)[2][2][4][2], const pg8::Unit& u, int wr, int wc, int fr, int fq) const {
;     ...
;                 f32x4 e0 = acc[ai][0][m][0] * c, e1 = acc[ai][0][m][1] * c;
; #pragma unroll
;                 for (int i = 0; i < 4; ++i) { e0[i] = __builtin_amdgcn_exp2f(e0[i]); e1[i] = __builtin_amdgcn_exp2f(e1[i]); }
;                 e0 = e0 + 1.0f; e1 = e1 + 1.0f;
; #pragma unroll
;                 for (int i = 0; i < 4; ++i) { e0[i] = __builtin_amdgcn_rcpf(e0[i]); e1[i] = __builtin_amdgcn_rcpf(e1[i]); }
;                 const f32x4 h0 = (acc[ai][0][m][0] * acc[ai][1][m][0]) * rs2 * e0, h1 = (acc[ai][0][m][1] * acc[ai][1][m][1]) * rs2 * e1;
.LBB0_1224:
	v_lshl_add_u32 v240, s20, 8, v148
	v_mov_b32_e32 v172, v240
	v_ashrrev_i32_e32 v173, 31, v172
	v_lshlrev_b64 v[172:173], 6, v[172:173]
	v_lshl_add_u64 v[172:173], v[134:135], 0, v[172:173]
	global_load_dwordx4 v[172:175], v[172:173], off
	v_add_u32_e32 v176, 16, v240
	v_ashrrev_i32_e32 v177, 31, v176
	v_lshlrev_b64 v[176:177], 6, v[176:177]
	v_lshl_add_u64 v[176:177], v[134:135], 0, v[176:177]
	global_load_dwordx4 v[176:179], v[176:177], off
	v_add_u32_e32 v180, 32, v240
	v_ashrrev_i32_e32 v181, 31, v180
	v_lshlrev_b64 v[180:181], 6, v[180:181]
	v_lshl_add_u64 v[180:181], v[134:135], 0, v[180:181]
	global_load_dwordx4 v[180:183], v[180:181], off
	v_add_u32_e32 v184, 48, v240
	v_ashrrev_i32_e32 v185, 31, v184
	v_lshlrev_b64 v[184:185], 6, v[184:185]
	v_lshl_add_u64 v[184:185], v[134:135], 0, v[184:185]
	global_load_dwordx4 v[184:187], v[184:185], off
	v_add_u32_e32 v188, 0x80, v240
	v_ashrrev_i32_e32 v189, 31, v188
	v_lshlrev_b64 v[188:189], 6, v[188:189]
	v_lshl_add_u64 v[188:189], v[134:135], 0, v[188:189]
	global_load_dwordx4 v[188:191], v[188:189], off
	v_add_u32_e32 v218, 0x90, v240
	v_ashrrev_i32_e32 v219, 31, v218
	v_lshlrev_b64 v[218:219], 6, v[218:219]
	v_lshl_add_u64 v[218:219], v[134:135], 0, v[218:219]
	global_load_dwordx4 v[218:221], v[218:219], off
	v_add_u32_e32 v222, 0xa0, v240
	v_ashrrev_i32_e32 v223, 31, v222
	v_lshlrev_b64 v[222:223], 6, v[222:223]
	v_lshl_add_u64 v[222:223], v[134:135], 0, v[222:223]
	global_load_dwordx4 v[222:225], v[222:223], off
	v_add_u32_e32 v226, 0xb0, v240
	v_ashrrev_i32_e32 v227, 31, v226
	v_lshlrev_b64 v[226:227], 6, v[226:227]
	v_lshl_add_u64 v[226:227], v[134:135], 0, v[226:227]
	global_load_dwordx4 v[226:229], v[226:227], off
	v_xor_b32_e32 v238, 16, v215
	v_xor_b32_e32 v239, 32, v215
	v_lshlrev_b32_e32 v238, 2, v238
	v_lshlrev_b32_e32 v239, 2, v239
	v_lshl_add_u32 v140, s20, 8, v148
	v_or_b32_e32 v146, 16, v140
	v_ashrrev_i32_e32 v141, 31, v140
	v_ashrrev_i32_e32 v147, 31, v146
	v_lshlrev_b64 v[142:143], 6, v[140:141]
	v_lshlrev_b64 v[144:145], 6, v[146:147]
	v_lshl_add_u64 v[142:143], v[134:135], 0, v[142:143]
	v_lshl_add_u64 v[144:145], v[134:135], 0, v[144:145]
	s_nop 0
	s_nop 0
	v_or_b32_e32 v144, 32, v140
	v_ashrrev_i32_e32 v145, 31, v144
	v_lshlrev_b64 v[142:143], 6, v[144:145]
	v_lshl_add_u64 v[142:143], v[134:135], 0, v[142:143]
	s_nop 0
	v_or_b32_e32 v142, 48, v140
	v_ashrrev_i32_e32 v143, 31, v142
	v_lshlrev_b64 v[164:165], 6, v[142:143]
	v_lshl_add_u64 v[164:165], v[134:135], 0, v[164:165]
	s_nop 0
	v_and_b32_e32 v143, 64, v215
	v_xor_b32_e32 v141, 16, v215
	v_add_u32_e32 v143, 64, v143
	v_xor_b32_e32 v145, 32, v215
	v_cmp_lt_i32_e32 vcc, v141, v143
	v_pk_mul_f32 v[126:127], v[118:119], v[126:127]
	v_pk_mul_f32 v[124:125], v[116:117], v[124:125]
	v_cndmask_b32_e32 v141, v215, v141, vcc
	v_cmp_lt_i32_e32 vcc, v145, v143
	v_lshlrev_b32_e32 v141, 2, v141
	v_pk_mul_f32 v[120:121], v[112:113], v[120:121]
	v_cndmask_b32_e32 v143, v215, v145, vcc
	v_lshlrev_b32_e32 v143, 2, v143
	v_pk_mul_f32 v[122:123], v[114:115], v[122:123]
	v_lshl_or_b32 v168, s66, 7, v150
	v_ashrrev_i32_e32 v169, 31, v168
	v_pk_mul_f32 v[100:101], v[108:109], v[100:101]
	v_pk_mul_f32 v[102:103], v[110:111], v[102:103]
	v_pk_mul_f32 v[98:99], v[106:107], v[98:99]
	v_pk_mul_f32 v[96:97], v[104:105], v[96:97]
	v_pk_mul_f32 v[84:85], v[92:93], v[84:85]
	v_pk_mul_f32 v[86:87], v[94:95], v[86:87]
	v_pk_mul_f32 v[82:83], v[90:91], v[82:83]
	v_pk_mul_f32 v[80:81], v[88:89], v[80:81]
	v_pk_mul_f32 v[68:69], v[76:77], v[68:69]
	v_pk_mul_f32 v[70:71], v[78:79], v[70:71]
	v_pk_mul_f32 v[66:67], v[74:75], v[66:67]
	v_pk_mul_f32 v[64:65], v[72:73], v[64:65]
	v_pk_mul_f32 v[52:53], v[60:61], v[52:53]
	v_pk_mul_f32 v[54:55], v[62:63], v[54:55]
	v_pk_mul_f32 v[50:51], v[58:59], v[50:51]
	v_pk_mul_f32 v[48:49], v[56:57], v[48:49]
	v_pk_mul_f32 v[36:37], v[44:45], v[36:37]
	v_pk_mul_f32 v[38:39], v[46:47], v[38:39]
	v_pk_mul_f32 v[34:35], v[42:43], v[34:35]
	v_pk_mul_f32 v[32:33], v[40:41], v[32:33]
	v_pk_mul_f32 v[20:21], v[28:29], v[20:21]
	v_pk_mul_f32 v[22:23], v[30:31], v[22:23]
	v_pk_mul_f32 v[18:19], v[26:27], v[18:19]
	v_pk_mul_f32 v[16:17], v[24:25], v[16:17]
	v_pk_mul_f32 v[4:5], v[12:13], v[4:5]
	v_pk_mul_f32 v[6:7], v[14:15], v[6:7]
	v_pk_mul_f32 v[2:3], v[10:11], v[2:3]
	v_pk_mul_f32 v[0:1], v[8:9], v[0:1]
	s_andn2_b64 vcc, exec, s[4:5]
	s_mov_b64 s[4:5], -1
	s_waitcnt vmcnt(0)
	v_add_f32_e32 v172, v172, v173
	v_add_f32_e32 v174, v174, v175
	v_add_f32_e32 v176, v176, v177
	v_add_f32_e32 v178, v178, v179
	v_add_f32_e32 v180, v180, v181
	v_add_f32_e32 v182, v182, v183
	v_add_f32_e32 v184, v184, v185
	v_add_f32_e32 v186, v186, v187
	v_add_f32_e32 v188, v188, v189
	v_add_f32_e32 v190, v190, v191
	v_add_f32_e32 v218, v218, v219
	v_add_f32_e32 v220, v220, v221
	v_add_f32_e32 v222, v222, v223
	v_add_f32_e32 v224, v224, v225
	v_add_f32_e32 v226, v226, v227
	v_add_f32_e32 v228, v228, v229
	v_add_f32_e32 v172, v172, v174
	v_add_f32_e32 v176, v176, v178
	v_add_f32_e32 v180, v180, v182
	v_add_f32_e32 v184, v184, v186
	v_add_f32_e32 v188, v188, v190
	v_add_f32_e32 v218, v218, v220
	v_add_f32_e32 v222, v222, v224
	v_add_f32_e32 v226, v226, v228
	ds_bpermute_b32 v173, v238, v172
	ds_bpermute_b32 v177, v238, v176
	ds_bpermute_b32 v181, v238, v180
	ds_bpermute_b32 v185, v238, v184
	ds_bpermute_b32 v189, v238, v188
	ds_bpermute_b32 v219, v238, v218
	ds_bpermute_b32 v223, v238, v222
	ds_bpermute_b32 v227, v238, v226
	s_waitcnt lgkmcnt(0)
; __device__ __forceinline__ v4u pack8(const f32x4 a, const f32x4 b) { v4u w; w.x = cvt_pk_bf16(a[0], a[1]); w.y = cvt_pk_bf16(a[2], a[3]); w.z = cvt_pk_bf16(b[0], b[1]); w.w = cvt_pk_bf16(b[2], b[3]); return w; }
; __device__ __forceinline__ void row_rstd4(const float* ssq, int row0, int fq, float (&rs)[4]) {
;     f32x4 v[4];
; #pragma unroll
;     for (int m = 0; m < 4; ++m) v[m] = *(const f32x4*)(ssq + (size_t)(row0 + m * 16) * 16 + fq * 4);
; #pragma unroll
;     for (int m = 0; m < 4; ++m) { float t = (v[m][0] + v[m][1]) + (v[m][2] + v[m][3]); t += __shfl_xor(t, 16); t += __shfl_xor(t, 32); rs[m] = __builtin_amdgcn_rsqf(t * (1.f / DM) + EPS); }
; }
;     __device__ __forceinline__ void operator()(const f32x4 (&acc)[2][2][4][2], const pg8::Unit& u, int wr, int wc, int fr, int fq) const {
;     ...
;                 const int row = row0 + ai * 128 + m * 16; const float rs = rsv[m], c = -rs * LOG2E, rs2 = rs * rs;
;                 f32x4 e0 = acc[ai][0][m][0] * c, e1 = acc[ai][0][m][1] * c;
; #pragma unroll
;                 for (int i = 0; i < 4; ++i) { e0[i] = __builtin_amdgcn_exp2f(e0[i]); e1[i] = __builtin_amdgcn_exp2f(e1[i]); }
;                 e0 = e0 + 1.0f; e1 = e1 + 1.0f;
; #pragma unroll
;                 for (int i = 0; i < 4; ++i) { e0[i] = __builtin_amdgcn_rcpf(e0[i]); e1[i] = __builtin_amdgcn_rcpf(e1[i]); }
;                 const f32x4 h0 = (acc[ai][0][m][0] * acc[ai][1][m][0]) * rs2 * e0, h1 = (acc[ai][0][m][1] * acc[ai][1][m][1]) * rs2 * e1;
;                 *(v4u*)(O + (size_t)row * FFH + col0) = pack8(h0, h1);
	v_add_f32_e32 v172, v172, v173
	v_add_f32_e32 v176, v176, v177
	v_add_f32_e32 v180, v180, v181
	v_add_f32_e32 v184, v184, v185
	v_add_f32_e32 v188, v188, v189
	v_add_f32_e32 v218, v218, v219
	v_add_f32_e32 v222, v222, v223
	v_add_f32_e32 v226, v226, v227
	ds_bpermute_b32 v173, v239, v172
	ds_bpermute_b32 v177, v239, v176
	ds_bpermute_b32 v181, v239, v180
	ds_bpermute_b32 v185, v239, v184
	ds_bpermute_b32 v189, v239, v188
	ds_bpermute_b32 v219, v239, v218
	ds_bpermute_b32 v223, v239, v222
	ds_bpermute_b32 v227, v239, v226
	s_waitcnt lgkmcnt(0)
	v_add_f32_e32 v172, v172, v173
	v_add_f32_e32 v176, v176, v177
	v_add_f32_e32 v180, v180, v181
	v_add_f32_e32 v184, v184, v185
	v_add_f32_e32 v188, v188, v189
	v_add_f32_e32 v218, v218, v219
	v_add_f32_e32 v222, v222, v223
	v_add_f32_e32 v226, v226, v227
	v_fmamk_f32 v172, v172, 0x3a800000, v212
	v_fmamk_f32 v176, v176, 0x3a800000, v212
	v_fmamk_f32 v180, v180, 0x3a800000, v212
	v_fmamk_f32 v184, v184, 0x3a800000, v212
	v_fmamk_f32 v188, v188, 0x3a800000, v212
	v_fmamk_f32 v218, v218, 0x3a800000, v212
	v_fmamk_f32 v222, v222, 0x3a800000, v212
	v_fmamk_f32 v226, v226, 0x3a800000, v212
	v_rsq_f32_e32 v230, v172
	v_rsq_f32_e32 v231, v176
	v_rsq_f32_e32 v232, v180
	v_rsq_f32_e32 v233, v184
	v_rsq_f32_e32 v234, v188
	v_rsq_f32_e32 v235, v218
	v_rsq_f32_e32 v236, v222
	v_rsq_f32_e32 v237, v226
	s_nop 0
	s_waitcnt lgkmcnt(0)
	s_nop 0
	s_nop 0
	s_nop 0
	s_nop 0
	s_nop 0
	s_nop 0
	s_nop 0
	s_nop 0
	s_nop 0
	s_nop 0
	s_nop 0
	s_nop 0
	s_nop 0
	s_nop 0
	s_nop 0
	s_nop 0
	s_nop 0
	s_nop 0
	s_nop 0
	s_nop 0
	s_nop 0
	s_nop 0
	s_nop 0
	s_nop 0
	s_waitcnt lgkmcnt(0)
	s_nop 0
	s_nop 0
	s_waitcnt lgkmcnt(0)
	s_nop 0
	s_waitcnt lgkmcnt(0)
	s_nop 0
	s_waitcnt lgkmcnt(0)
	s_nop 0
	s_nop 0
	s_nop 0
	s_nop 0
	s_waitcnt lgkmcnt(0)
	s_nop 0
	s_nop 0
	s_waitcnt lgkmcnt(0)
	s_nop 0
	s_waitcnt lgkmcnt(0)
	s_nop 0
	s_waitcnt lgkmcnt(0)
	s_nop 0
	v_mov_b32_e32 v145, v230
	s_nop 0
	v_mov_b32_e32 v153, v233
	s_nop 0
	v_mov_b32_e32 v155, v232
	v_mul_f32_e32 v152, 0xbfb8aa3b, v145
	v_pk_mul_f32 v[118:119], v[118:119], v[152:153] op_sel_hi:[1,0]
	v_pk_mul_f32 v[116:117], v[116:117], v[152:153] op_sel_hi:[1,0]
	v_pk_mul_f32 v[112:113], v[112:113], v[152:153] op_sel_hi:[1,0]
	v_pk_mul_f32 v[114:115], v[114:115], v[152:153] op_sel_hi:[1,0]
	v_exp_f32_e32 v116, v116
	v_exp_f32_e32 v112, v112
	v_exp_f32_e32 v117, v117
	v_exp_f32_e32 v118, v118
	v_exp_f32_e32 v119, v119
	v_exp_f32_e32 v113, v113
	v_exp_f32_e32 v114, v114
	v_exp_f32_e32 v115, v115
	v_pk_add_f32 v[118:119], v[118:119], 1.0 op_sel_hi:[1,0]
	v_pk_add_f32 v[116:117], v[116:117], 1.0 op_sel_hi:[1,0]
	v_pk_add_f32 v[112:113], v[112:113], 1.0 op_sel_hi:[1,0]
	v_pk_add_f32 v[114:115], v[114:115], 1.0 op_sel_hi:[1,0]
	v_rcp_f32_e32 v116, v116
	v_rcp_f32_e32 v112, v112
	v_rcp_f32_e32 v117, v117
	v_rcp_f32_e32 v118, v118
	v_rcp_f32_e32 v119, v119
	v_rcp_f32_e32 v113, v113
	v_rcp_f32_e32 v114, v114
	v_rcp_f32_e32 v115, v115
	v_mul_f32_e32 v154, v145, v145
	s_nop 0
	v_pk_mul_f32 v[124:125], v[124:125], v[154:155] op_sel_hi:[1,0]
	v_pk_mul_f32 v[126:127], v[126:127], v[154:155] op_sel_hi:[1,0]
	v_pk_mul_f32 v[120:121], v[120:121], v[154:155] op_sel_hi:[1,0]
	v_mov_b32_e32 v147, v231
	v_pk_mul_f32 v[122:123], v[122:123], v[154:155] op_sel_hi:[1,0]
	v_pk_mul_f32 v[118:119], v[126:127], v[118:119]
	v_pk_mul_f32 v[116:117], v[124:125], v[116:117]
	v_pk_mul_f32 v[112:113], v[120:121], v[112:113]
	v_pk_mul_f32 v[114:115], v[122:123], v[114:115]
	v_cvt_pk_bf16_f32 v116, v116, v117
	v_cvt_pk_bf16_f32 v117, v118, v119
	v_cvt_pk_bf16_f32 v118, v112, v113
	v_mov_b64_e32 v[112:113], s[8:9]
	v_cvt_pk_bf16_f32 v119, v114, v115
	v_mad_i64_i32 v[120:121], s[22:23], v140, s3, v[112:113]
	v_lshlrev_b64 v[114:115], 1, v[168:169]
	v_lshl_add_u64 v[120:121], v[120:121], 0, v[114:115]
	global_store_dwordx4 v[120:121], v[116:119], off
	v_mul_f32_e32 v124, v147, v147
	v_pk_mul_f32 v[100:101], v[100:101], v[124:125] op_sel_hi:[1,0]
	v_mul_f32_e32 v116, 0xbfb8aa3b, v147
	v_pk_mul_f32 v[120:121], v[108:109], v[116:117] op_sel_hi:[1,0]
	v_pk_mul_f32 v[118:119], v[110:111], v[116:117] op_sel_hi:[1,0]
	v_pk_mul_f32 v[122:123], v[106:107], v[116:117] op_sel_hi:[1,0]
	v_pk_mul_f32 v[116:117], v[104:105], v[116:117] op_sel_hi:[1,0]
	v_exp_f32_e32 v120, v120
	v_exp_f32_e32 v121, v121
	v_exp_f32_e32 v116, v116
	v_exp_f32_e32 v118, v118
	v_exp_f32_e32 v119, v119
	v_exp_f32_e32 v122, v122
	v_exp_f32_e32 v123, v123
	v_exp_f32_e32 v117, v117
	v_pk_add_f32 v[120:121], v[120:121], 1.0 op_sel_hi:[1,0]
	v_pk_add_f32 v[118:119], v[118:119], 1.0 op_sel_hi:[1,0]
	v_pk_add_f32 v[122:123], v[122:123], 1.0 op_sel_hi:[1,0]
	v_pk_add_f32 v[116:117], v[116:117], 1.0 op_sel_hi:[1,0]
	v_rcp_f32_e32 v120, v120
	v_rcp_f32_e32 v121, v121
	v_rcp_f32_e32 v116, v116
	v_rcp_f32_e32 v117, v117
	v_rcp_f32_e32 v118, v118
	v_rcp_f32_e32 v122, v122
	v_rcp_f32_e32 v119, v119
	v_rcp_f32_e32 v123, v123
	v_pk_mul_f32 v[102:103], v[102:103], v[124:125] op_sel_hi:[1,0]
	v_pk_mul_f32 v[100:101], v[100:101], v[120:121]
	v_pk_mul_f32 v[96:97], v[96:97], v[124:125] op_sel_hi:[1,0]
	v_pk_mul_f32 v[98:99], v[98:99], v[124:125] op_sel_hi:[1,0]
	v_pk_mul_f32 v[102:103], v[102:103], v[118:119]
	v_pk_mul_f32 v[104:105], v[98:99], v[122:123]
	v_pk_mul_f32 v[98:99], v[96:97], v[116:117]
	v_cvt_pk_bf16_f32 v96, v100, v101
	v_mad_i64_i32 v[100:101], s[22:23], v146, s3, v[112:113]
	v_cvt_pk_bf16_f32 v97, v102, v103
	v_cvt_pk_bf16_f32 v98, v98, v99
	v_cvt_pk_bf16_f32 v99, v104, v105
	v_lshl_add_u64 v[100:101], v[100:101], 0, v[114:115]
	global_store_dwordx4 v[100:101], v[96:99], off
	v_mul_f32_e32 v104, v155, v155
	v_pk_mul_f32 v[84:85], v[84:85], v[104:105] op_sel_hi:[1,0]
; __device__ __forceinline__ v4u pack8(const f32x4 a, const f32x4 b) { v4u w; w.x = cvt_pk_bf16(a[0], a[1]); w.y = cvt_pk_bf16(a[2], a[3]); w.z = cvt_pk_bf16(b[0], b[1]); w.w = cvt_pk_bf16(b[2], b[3]); return w; }
; __device__ __forceinline__ void row_rstd4(const float* ssq, int row0, int fq, float (&rs)[4]) {
;     ...
;     for (int m = 0; m < 4; ++m) v[m] = *(const f32x4*)(ssq + (size_t)(row0 + m * 16) * 16 + fq * 4);
; #pragma unroll
;     for (int m = 0; m < 4; ++m) { float t = (v[m][0] + v[m][1]) + (v[m][2] + v[m][3]); t += __shfl_xor(t, 16); t += __shfl_xor(t, 32); rs[m] = __builtin_amdgcn_rsqf(t * (1.f / DM) + EPS); }
;     __device__ __forceinline__ void operator()(const f32x4 (&acc)[2][2][4][2], const pg8::Unit& u, int wr, int wc, int fr, int fq) const {
;     ...
;                 const int row = row0 + ai * 128 + m * 16; const float rs = rsv[m], c = -rs * LOG2E, rs2 = rs * rs;
;                 f32x4 e0 = acc[ai][0][m][0] * c, e1 = acc[ai][0][m][1] * c;
; #pragma unroll
;                 for (int i = 0; i < 4; ++i) { e0[i] = __builtin_amdgcn_exp2f(e0[i]); e1[i] = __builtin_amdgcn_exp2f(e1[i]); }
;                 e0 = e0 + 1.0f; e1 = e1 + 1.0f;
; #pragma unroll
;                 for (int i = 0; i < 4; ++i) { e0[i] = __builtin_amdgcn_rcpf(e0[i]); e1[i] = __builtin_amdgcn_rcpf(e1[i]); }
;                 const f32x4 h0 = (acc[ai][0][m][0] * acc[ai][1][m][0]) * rs2 * e0, h1 = (acc[ai][0][m][1] * acc[ai][1][m][1]) * rs2 * e1;
;                 *(v4u*)(O + (size_t)row * FFH + col0) = pack8(h0, h1);
	v_mul_f32_e32 v96, 0xbfb8aa3b, v155
	v_pk_mul_f32 v[100:101], v[92:93], v[96:97] op_sel_hi:[1,0]
	v_pk_mul_f32 v[98:99], v[94:95], v[96:97] op_sel_hi:[1,0]
	v_pk_mul_f32 v[102:103], v[90:91], v[96:97] op_sel_hi:[1,0]
	v_pk_mul_f32 v[96:97], v[88:89], v[96:97] op_sel_hi:[1,0]
	v_exp_f32_e32 v100, v100
	v_exp_f32_e32 v101, v101
	v_exp_f32_e32 v96, v96
	v_exp_f32_e32 v98, v98
	v_exp_f32_e32 v99, v99
	v_exp_f32_e32 v102, v102
	v_exp_f32_e32 v103, v103
	v_exp_f32_e32 v97, v97
	v_pk_add_f32 v[100:101], v[100:101], 1.0 op_sel_hi:[1,0]
	v_pk_add_f32 v[98:99], v[98:99], 1.0 op_sel_hi:[1,0]
	v_pk_add_f32 v[102:103], v[102:103], 1.0 op_sel_hi:[1,0]
	v_pk_add_f32 v[96:97], v[96:97], 1.0 op_sel_hi:[1,0]
	v_rcp_f32_e32 v100, v100
	v_rcp_f32_e32 v101, v101
	v_rcp_f32_e32 v96, v96
	v_rcp_f32_e32 v97, v97
	v_rcp_f32_e32 v98, v98
	v_rcp_f32_e32 v102, v102
	v_rcp_f32_e32 v99, v99
	v_rcp_f32_e32 v103, v103
	v_pk_mul_f32 v[86:87], v[86:87], v[104:105] op_sel_hi:[1,0]
	v_pk_mul_f32 v[84:85], v[84:85], v[100:101]
	v_pk_mul_f32 v[80:81], v[80:81], v[104:105] op_sel_hi:[1,0]
	v_pk_mul_f32 v[82:83], v[82:83], v[104:105] op_sel_hi:[1,0]
	v_pk_mul_f32 v[86:87], v[86:87], v[98:99]
	v_pk_mul_f32 v[88:89], v[82:83], v[102:103]
	v_pk_mul_f32 v[82:83], v[80:81], v[96:97]
	v_cvt_pk_bf16_f32 v80, v84, v85
	v_mad_i64_i32 v[84:85], s[22:23], v144, s3, v[112:113]
	v_cvt_pk_bf16_f32 v81, v86, v87
	v_cvt_pk_bf16_f32 v82, v82, v83
	v_cvt_pk_bf16_f32 v83, v88, v89
	v_lshl_add_u64 v[84:85], v[84:85], 0, v[114:115]
	global_store_dwordx4 v[84:85], v[80:83], off
	v_mul_f32_e32 v88, v153, v153
	v_pk_mul_f32 v[68:69], v[68:69], v[88:89] op_sel_hi:[1,0]
	v_mul_f32_e32 v80, 0xbfb8aa3b, v153
	v_pk_mul_f32 v[84:85], v[76:77], v[80:81] op_sel_hi:[1,0]
	v_pk_mul_f32 v[82:83], v[78:79], v[80:81] op_sel_hi:[1,0]
	v_pk_mul_f32 v[86:87], v[74:75], v[80:81] op_sel_hi:[1,0]
	v_pk_mul_f32 v[80:81], v[72:73], v[80:81] op_sel_hi:[1,0]
	v_exp_f32_e32 v84, v84
	v_exp_f32_e32 v85, v85
	v_exp_f32_e32 v80, v80
	v_exp_f32_e32 v82, v82
	v_exp_f32_e32 v83, v83
	v_exp_f32_e32 v86, v86
	v_exp_f32_e32 v87, v87
	v_exp_f32_e32 v81, v81
	v_pk_add_f32 v[84:85], v[84:85], 1.0 op_sel_hi:[1,0]
	v_pk_add_f32 v[82:83], v[82:83], 1.0 op_sel_hi:[1,0]
	v_pk_add_f32 v[86:87], v[86:87], 1.0 op_sel_hi:[1,0]
	v_pk_add_f32 v[80:81], v[80:81], 1.0 op_sel_hi:[1,0]
	v_rcp_f32_e32 v84, v84
	v_rcp_f32_e32 v85, v85
	v_rcp_f32_e32 v80, v80
	v_rcp_f32_e32 v81, v81
	v_rcp_f32_e32 v82, v82
	v_rcp_f32_e32 v86, v86
	v_rcp_f32_e32 v83, v83
	v_rcp_f32_e32 v87, v87
	v_pk_mul_f32 v[70:71], v[70:71], v[88:89] op_sel_hi:[1,0]
	v_pk_mul_f32 v[68:69], v[68:69], v[84:85]
	v_pk_mul_f32 v[64:65], v[64:65], v[88:89] op_sel_hi:[1,0]
	v_pk_mul_f32 v[66:67], v[66:67], v[88:89] op_sel_hi:[1,0]
	v_pk_mul_f32 v[70:71], v[70:71], v[82:83]
	v_pk_mul_f32 v[72:73], v[66:67], v[86:87]
	v_pk_mul_f32 v[66:67], v[64:65], v[80:81]
	v_cvt_pk_bf16_f32 v64, v68, v69
	v_mad_i64_i32 v[68:69], s[22:23], v142, s3, v[112:113]
	v_add_u32_e32 v84, 0x80, v140
	v_cvt_pk_bf16_f32 v65, v70, v71
	v_cvt_pk_bf16_f32 v66, v66, v67
	v_cvt_pk_bf16_f32 v67, v72, v73
	v_lshl_add_u64 v[68:69], v[68:69], 0, v[114:115]
	v_ashrrev_i32_e32 v85, 31, v84
	global_store_dwordx4 v[68:69], v[64:67], off
	v_add_u32_e32 v86, 0x90, v140
	v_ashrrev_i32_e32 v87, 31, v86
	v_lshlrev_b64 v[64:65], 6, v[84:85]
	v_lshl_add_u64 v[64:65], v[134:135], 0, v[64:65]
	s_nop 0
	v_lshlrev_b64 v[64:65], 6, v[86:87]
	v_lshl_add_u64 v[64:65], v[134:135], 0, v[64:65]
	s_nop 0
	v_add_u32_e32 v66, 0xa0, v140
	v_ashrrev_i32_e32 v67, 31, v66
	v_lshlrev_b64 v[64:65], 6, v[66:67]
	v_lshl_add_u64 v[64:65], v[134:135], 0, v[64:65]
	s_nop 0
	v_add_u32_e32 v64, 0xb0, v140
	v_ashrrev_i32_e32 v65, 31, v64
	v_lshlrev_b64 v[80:81], 6, v[64:65]
	v_lshl_add_u64 v[80:81], v[134:135], 0, v[80:81]
	s_nop 0
	s_waitcnt lgkmcnt(0)
	s_nop 0
	s_nop 0
	s_nop 0
	s_nop 0
	s_nop 0
	s_nop 0
	s_nop 0
	s_nop 0
	s_nop 0
	s_nop 0
	s_nop 0
	s_waitcnt lgkmcnt(0)
	s_nop 0
	s_nop 0
	s_nop 0
	s_nop 0
	s_waitcnt lgkmcnt(0)
	s_nop 0
	s_waitcnt lgkmcnt(0)
	s_nop 0
	s_nop 0
	s_nop 0
	s_nop 0
	s_nop 0
	s_nop 0
	s_nop 0
	s_nop 0
	s_nop 0
	s_nop 0
	s_nop 0
	s_nop 0
	s_nop 0
	s_nop 0
	s_waitcnt lgkmcnt(0)
	s_nop 0
	s_nop 0
	s_waitcnt lgkmcnt(0)
	s_nop 0
	s_nop 0
	s_waitcnt lgkmcnt(0)
	s_nop 0
	s_nop 0
	v_mov_b32_e32 v65, v234
	s_nop 0
	s_waitcnt lgkmcnt(0)
	s_nop 0
	s_nop 0
	s_waitcnt lgkmcnt(0)
; __device__ __forceinline__ v4u pack8(const f32x4 a, const f32x4 b) { v4u w; w.x = cvt_pk_bf16(a[0], a[1]); w.y = cvt_pk_bf16(a[2], a[3]); w.z = cvt_pk_bf16(b[0], b[1]); w.w = cvt_pk_bf16(b[2], b[3]); return w; }
;     __device__ __forceinline__ void operator()(const f32x4 (&acc)[2][2][4][2], const pg8::Unit& u, int wr, int wc, int fr, int fq) const {
;     ...
;                 const int row = row0 + ai * 128 + m * 16; const float rs = rsv[m], c = -rs * LOG2E, rs2 = rs * rs;
;                 f32x4 e0 = acc[ai][0][m][0] * c, e1 = acc[ai][0][m][1] * c;
; #pragma unroll
;                 for (int i = 0; i < 4; ++i) { e0[i] = __builtin_amdgcn_exp2f(e0[i]); e1[i] = __builtin_amdgcn_exp2f(e1[i]); }
;                 e0 = e0 + 1.0f; e1 = e1 + 1.0f;
; #pragma unroll
;                 for (int i = 0; i < 4; ++i) { e0[i] = __builtin_amdgcn_rcpf(e0[i]); e1[i] = __builtin_amdgcn_rcpf(e1[i]); }
;                 const f32x4 h0 = (acc[ai][0][m][0] * acc[ai][1][m][0]) * rs2 * e0, h1 = (acc[ai][0][m][1] * acc[ai][1][m][1]) * rs2 * e1;
;                 *(v4u*)(O + (size_t)row * FFH + col0) = pack8(h0, h1);
	s_nop 0
	s_nop 0
	v_mov_b32_e32 v78, v237
	v_mul_f32_e32 v68, 0xbfb8aa3b, v65
	v_pk_mul_f32 v[72:73], v[60:61], v[68:69] op_sel_hi:[1,0]
	v_mov_b32_e32 v77, v236
	v_pk_mul_f32 v[70:71], v[62:63], v[68:69] op_sel_hi:[1,0]
	v_pk_mul_f32 v[74:75], v[58:59], v[68:69] op_sel_hi:[1,0]
	v_pk_mul_f32 v[68:69], v[56:57], v[68:69] op_sel_hi:[1,0]
	v_exp_f32_e32 v72, v72
	v_exp_f32_e32 v73, v73
	v_exp_f32_e32 v68, v68
	v_exp_f32_e32 v70, v70
	v_exp_f32_e32 v71, v71
	v_exp_f32_e32 v74, v74
	v_exp_f32_e32 v75, v75
	v_exp_f32_e32 v69, v69
	v_pk_add_f32 v[72:73], v[72:73], 1.0 op_sel_hi:[1,0]
	v_pk_add_f32 v[70:71], v[70:71], 1.0 op_sel_hi:[1,0]
	v_pk_add_f32 v[74:75], v[74:75], 1.0 op_sel_hi:[1,0]
	v_pk_add_f32 v[68:69], v[68:69], 1.0 op_sel_hi:[1,0]
	v_rcp_f32_e32 v72, v72
	v_rcp_f32_e32 v73, v73
	v_rcp_f32_e32 v68, v68
	v_rcp_f32_e32 v69, v69
	v_rcp_f32_e32 v70, v70
	v_rcp_f32_e32 v74, v74
	v_rcp_f32_e32 v71, v71
	v_rcp_f32_e32 v75, v75
	v_mul_f32_e32 v76, v65, v65
	v_mov_b32_e32 v67, v235
	v_pk_mul_f32 v[52:53], v[52:53], v[76:77] op_sel_hi:[1,0]
	v_pk_mul_f32 v[54:55], v[54:55], v[76:77] op_sel_hi:[1,0]
	v_pk_mul_f32 v[52:53], v[52:53], v[72:73]
	v_pk_mul_f32 v[48:49], v[48:49], v[76:77] op_sel_hi:[1,0]
	v_pk_mul_f32 v[50:51], v[50:51], v[76:77] op_sel_hi:[1,0]
	v_pk_mul_f32 v[54:55], v[54:55], v[70:71]
	v_pk_mul_f32 v[56:57], v[50:51], v[74:75]
	v_pk_mul_f32 v[50:51], v[48:49], v[68:69]
	v_cvt_pk_bf16_f32 v48, v52, v53
	v_mad_i64_i32 v[52:53], s[22:23], v84, s3, v[112:113]
	v_cvt_pk_bf16_f32 v49, v54, v55
	v_cvt_pk_bf16_f32 v50, v50, v51
	v_cvt_pk_bf16_f32 v51, v56, v57
	v_lshl_add_u64 v[52:53], v[52:53], 0, v[114:115]
	global_store_dwordx4 v[52:53], v[48:51], off
	v_mul_f32_e32 v56, v67, v67
	v_pk_mul_f32 v[36:37], v[36:37], v[56:57] op_sel_hi:[1,0]
	v_mul_f32_e32 v48, 0xbfb8aa3b, v67
	v_pk_mul_f32 v[52:53], v[44:45], v[48:49] op_sel_hi:[1,0]
	v_pk_mul_f32 v[50:51], v[46:47], v[48:49] op_sel_hi:[1,0]
	v_pk_mul_f32 v[54:55], v[42:43], v[48:49] op_sel_hi:[1,0]
	v_pk_mul_f32 v[48:49], v[40:41], v[48:49] op_sel_hi:[1,0]
	v_exp_f32_e32 v52, v52
	v_exp_f32_e32 v53, v53
	v_exp_f32_e32 v48, v48
	v_exp_f32_e32 v50, v50
	v_exp_f32_e32 v51, v51
	v_exp_f32_e32 v54, v54
	v_exp_f32_e32 v55, v55
	v_exp_f32_e32 v49, v49
	v_pk_add_f32 v[52:53], v[52:53], 1.0 op_sel_hi:[1,0]
	v_pk_add_f32 v[50:51], v[50:51], 1.0 op_sel_hi:[1,0]
	v_pk_add_f32 v[54:55], v[54:55], 1.0 op_sel_hi:[1,0]
	v_pk_add_f32 v[48:49], v[48:49], 1.0 op_sel_hi:[1,0]
	v_rcp_f32_e32 v52, v52
	v_rcp_f32_e32 v53, v53
	v_rcp_f32_e32 v48, v48
	v_rcp_f32_e32 v49, v49
	v_rcp_f32_e32 v50, v50
	v_rcp_f32_e32 v54, v54
	v_rcp_f32_e32 v51, v51
	v_rcp_f32_e32 v55, v55
	v_pk_mul_f32 v[38:39], v[38:39], v[56:57] op_sel_hi:[1,0]
	v_pk_mul_f32 v[36:37], v[36:37], v[52:53]
	v_pk_mul_f32 v[32:33], v[32:33], v[56:57] op_sel_hi:[1,0]
	v_pk_mul_f32 v[34:35], v[34:35], v[56:57] op_sel_hi:[1,0]
	v_pk_mul_f32 v[38:39], v[38:39], v[50:51]
	v_pk_mul_f32 v[40:41], v[34:35], v[54:55]
	v_pk_mul_f32 v[34:35], v[32:33], v[48:49]
	v_cvt_pk_bf16_f32 v32, v36, v37
	v_mad_i64_i32 v[36:37], s[22:23], v86, s3, v[112:113]
	v_cvt_pk_bf16_f32 v33, v38, v39
	v_cvt_pk_bf16_f32 v34, v34, v35
	v_cvt_pk_bf16_f32 v35, v40, v41
	v_lshl_add_u64 v[36:37], v[36:37], 0, v[114:115]
	global_store_dwordx4 v[36:37], v[32:35], off
	v_mul_f32_e32 v40, v77, v77
	v_pk_mul_f32 v[20:21], v[20:21], v[40:41] op_sel_hi:[1,0]
	v_mul_f32_e32 v32, 0xbfb8aa3b, v77
	v_pk_mul_f32 v[36:37], v[28:29], v[32:33] op_sel_hi:[1,0]
	v_pk_mul_f32 v[34:35], v[30:31], v[32:33] op_sel_hi:[1,0]
	v_pk_mul_f32 v[38:39], v[26:27], v[32:33] op_sel_hi:[1,0]
	v_pk_mul_f32 v[32:33], v[24:25], v[32:33] op_sel_hi:[1,0]
	v_exp_f32_e32 v36, v36
	v_exp_f32_e32 v37, v37
	v_exp_f32_e32 v32, v32
	v_exp_f32_e32 v34, v34
	v_exp_f32_e32 v35, v35
	v_exp_f32_e32 v38, v38
	v_exp_f32_e32 v39, v39
	v_exp_f32_e32 v33, v33
	v_pk_add_f32 v[36:37], v[36:37], 1.0 op_sel_hi:[1,0]
	v_pk_add_f32 v[34:35], v[34:35], 1.0 op_sel_hi:[1,0]
	v_pk_add_f32 v[38:39], v[38:39], 1.0 op_sel_hi:[1,0]
	v_pk_add_f32 v[32:33], v[32:33], 1.0 op_sel_hi:[1,0]
	v_rcp_f32_e32 v36, v36
	v_rcp_f32_e32 v37, v37
	v_rcp_f32_e32 v32, v32
	v_rcp_f32_e32 v33, v33
	v_rcp_f32_e32 v34, v34
	v_rcp_f32_e32 v38, v38
	v_rcp_f32_e32 v35, v35
	v_rcp_f32_e32 v39, v39
	v_pk_mul_f32 v[22:23], v[22:23], v[40:41] op_sel_hi:[1,0]
	v_pk_mul_f32 v[20:21], v[20:21], v[36:37]
	v_pk_mul_f32 v[16:17], v[16:17], v[40:41] op_sel_hi:[1,0]
	v_pk_mul_f32 v[18:19], v[18:19], v[40:41] op_sel_hi:[1,0]
	v_pk_mul_f32 v[22:23], v[22:23], v[34:35]
	v_pk_mul_f32 v[24:25], v[18:19], v[38:39]
	v_pk_mul_f32 v[18:19], v[16:17], v[32:33]
	v_cvt_pk_bf16_f32 v16, v20, v21
	v_mad_i64_i32 v[20:21], s[22:23], v66, s3, v[112:113]
	v_cvt_pk_bf16_f32 v17, v22, v23
	v_cvt_pk_bf16_f32 v18, v18, v19
	v_cvt_pk_bf16_f32 v19, v24, v25
	v_lshl_add_u64 v[20:21], v[20:21], 0, v[114:115]
	global_store_dwordx4 v[20:21], v[16:19], off
	v_mul_f32_e32 v24, v78, v78
	v_pk_mul_f32 v[4:5], v[4:5], v[24:25] op_sel_hi:[1,0]
	v_mul_f32_e32 v16, 0xbfb8aa3b, v78
	v_pk_mul_f32 v[20:21], v[12:13], v[16:17] op_sel_hi:[1,0]
	v_pk_mul_f32 v[18:19], v[14:15], v[16:17] op_sel_hi:[1,0]
	v_pk_mul_f32 v[22:23], v[10:11], v[16:17] op_sel_hi:[1,0]
	v_pk_mul_f32 v[16:17], v[8:9], v[16:17] op_sel_hi:[1,0]
	v_exp_f32_e32 v20, v20
	v_exp_f32_e32 v21, v21
	v_exp_f32_e32 v16, v16
	v_exp_f32_e32 v18, v18
	v_exp_f32_e32 v19, v19
	v_exp_f32_e32 v22, v22
	v_exp_f32_e32 v23, v23
	v_exp_f32_e32 v17, v17
	v_pk_add_f32 v[20:21], v[20:21], 1.0 op_sel_hi:[1,0]
	v_pk_add_f32 v[18:19], v[18:19], 1.0 op_sel_hi:[1,0]
	v_pk_add_f32 v[22:23], v[22:23], 1.0 op_sel_hi:[1,0]
	v_pk_add_f32 v[16:17], v[16:17], 1.0 op_sel_hi:[1,0]
	v_rcp_f32_e32 v20, v20
	v_rcp_f32_e32 v21, v21
	v_rcp_f32_e32 v16, v16
	v_rcp_f32_e32 v17, v17
	v_rcp_f32_e32 v18, v18
	v_rcp_f32_e32 v22, v22
	v_rcp_f32_e32 v19, v19
	v_rcp_f32_e32 v23, v23
	v_pk_mul_f32 v[6:7], v[6:7], v[24:25] op_sel_hi:[1,0]
	v_pk_mul_f32 v[4:5], v[4:5], v[20:21]
	v_pk_mul_f32 v[0:1], v[0:1], v[24:25] op_sel_hi:[1,0]
	v_pk_mul_f32 v[2:3], v[2:3], v[24:25] op_sel_hi:[1,0]
	v_pk_mul_f32 v[6:7], v[6:7], v[18:19]
	v_pk_mul_f32 v[8:9], v[2:3], v[22:23]
	v_pk_mul_f32 v[2:3], v[0:1], v[16:17]
	v_cvt_pk_bf16_f32 v0, v4, v5
	v_mad_i64_i32 v[4:5], s[22:23], v64, s3, v[112:113]
	v_cvt_pk_bf16_f32 v1, v6, v7
	v_cvt_pk_bf16_f32 v2, v2, v3
	v_cvt_pk_bf16_f32 v3, v8, v9
	v_lshl_add_u64 v[4:5], v[4:5], 0, v[114:115]
	global_store_dwordx4 v[4:5], v[0:3], off
	s_cbranch_vccnz .LBB0_1217
	s_andn2_b64 vcc, exec, s[6:7]
	s_cbranch_vccnz .LBB0_1216
	s_barrier
	s_branch .LBB0_1216
